# sample-attn: key-128 score via lane-parallel product + DPP reduce (drops 16 broadcast LDS reads), P.V with v_pk_fma_f32 on two pair accumulators
# speedup vs baseline: 1.0048x; 1.0048x over previous
.LBB0_754:
	s_or_b64 exec, exec, s[10:11]
	s_bitset1_b32 s4, 14
	s_ashr_i32 s10, s16, 6
	s_mul_i32 s12, s4, 0x600
	s_mul_hi_u32 s11, s4, 0x600
	s_add_u32 s12, s26, s12
	s_addc_u32 s13, s27, s11
	v_lshl_add_u64 v[0:1], v[8:9], 1, s[12:13]
	s_mov_b32 s11, 0x6a80000
	v_add_co_u32_e32 v0, vcc, s11, v0
	v_readlane_b32 s17, v255, 53
	s_nop 0
	v_addc_co_u32_e32 v1, vcc, 0, v1, vcc
	v_lshl_add_u32 v1, v8, 2, s17
	s_add_i32 s11, s10, 1
	v_and_b32_e32 v64, 63, v8
	v_mov_b32_e32 v0, v209
	v_lshlrev_b32_e32 v0, 16, v0
	ds_write_b32 v1, v0
	v_cvt_f32_i32_e32 v0, s11
	s_mov_b32 s11, 0x42fc0000
	s_waitcnt lgkmcnt(0)
	s_barrier
	v_cmp_lt_f32_e32 vcc, s11, v0
	s_and_b64 s[12:13], vcc, exec
	s_cselect_b32 s11, 0xffffffc0, 0
	v_cndmask_b32_e32 v1, 0, v242, vcc
	s_add_i32 s12, s10, s58
	v_sub_f32_e32 v0, v1, v0
	s_ashr_i32 s13, s12, 31
	v_exp_f32_e32 v0, v0
	s_lshl_b64 s[12:13], s[12:13], 2
	s_add_u32 s12, s22, s12
	s_addc_u32 s13, s23, s13
	global_load_dword v65, v175, s[12:13]
	s_and_b32 s12, s16, 0xffffff00
	s_and_b32 s24, s16, 0xffffffc0
	v_ldexp_f32 v0, v0, s11
	s_add_i32 s11, s12, 0
	s_lshl_b32 s13, s24, 2
	s_add_i32 s13, s17, s13
	v_mul_f32_e32 v66, 0x3fb8aa3b, v0
	v_mov_b32_e32 v0, s11
	v_mad_u32_u24 v67, v64, s72, v0
	v_mov_b32_e32 v44, s13
	v_lshl_add_u32 v185, v64, 2, s13
	ds_read_b32 v199, v185
	ds_read_b128 v[28:31], v44
	ds_read_b128 v[8:11], v44 offset:16
	ds_read_b128 v[4:7], v44 offset:32
	ds_read_b128 v[0:3], v44 offset:48
	ds_read_b128 v[24:27], v44 offset:64
	ds_read_b128 v[16:19], v44 offset:80
	ds_read_b128 v[20:23], v44 offset:96
	ds_read_b128 v[12:15], v44 offset:112
	ds_read_b128 v[48:51], v44 offset:128
	ds_read_b128 v[32:35], v44 offset:144
	ds_read_b128 v[52:55], v44 offset:160
	ds_read_b128 v[36:39], v44 offset:176
	ds_read_b128 v[56:59], v44 offset:192
	ds_read_b128 v[40:43], v44 offset:208
	ds_read_b128 v[60:63], v44 offset:224
	ds_read_b128 v[44:47], v44 offset:240
	s_add_i32 s13, s11, 0x10800
	v_lshl_add_u32 v184, v64, 2, s13
	ds_read_b32 v198, v184
	v_cmp_eq_u32_e32 vcc, 0, v64
	ds_read_b128 v[116:119], v67
	ds_read_b128 v[120:123], v67 offset:16
	ds_read_b128 v[124:127], v67 offset:32
	ds_read_b128 v[128:131], v67 offset:48
	ds_read_b128 v[132:135], v67 offset:64
	ds_read_b128 v[136:139], v67 offset:80
	ds_read_b128 v[140:143], v67 offset:96
	ds_read_b128 v[144:147], v67 offset:112
	ds_read_b128 v[148:151], v67 offset:128
	ds_read_b128 v[152:155], v67 offset:144
	ds_read_b128 v[156:159], v67 offset:160
	ds_read_b128 v[160:163], v67 offset:176
	v_sub_u32_e32 v69, 0x80, v64
	v_cvt_f32_ubyte0_e32 v69, v69
	v_or_b32_e32 v70, 64, v64
	v_sub_u32_e32 v70, 0x80, v70
	v_cvt_f32_ubyte0_e32 v70, v70
	s_waitcnt lgkmcnt(11)
	v_pk_mul_f32 v[186:187], v[28:29], v[116:117]
	v_pk_mul_f32 v[188:189], v[30:31], v[118:119]
	ds_read_b128 v[116:119], v67 offset:192
	s_waitcnt lgkmcnt(11)
	v_pk_fma_f32 v[186:187], v[8:9], v[120:121], v[186:187]
	v_pk_fma_f32 v[188:189], v[10:11], v[122:123], v[188:189]
	ds_read_b128 v[120:123], v67 offset:208
	s_waitcnt lgkmcnt(11)
	v_pk_fma_f32 v[186:187], v[4:5], v[124:125], v[186:187]
	v_pk_fma_f32 v[188:189], v[6:7], v[126:127], v[188:189]
	ds_read_b128 v[124:127], v67 offset:224
	s_waitcnt lgkmcnt(11)
	v_pk_fma_f32 v[186:187], v[0:1], v[128:129], v[186:187]
	v_pk_fma_f32 v[188:189], v[2:3], v[130:131], v[188:189]
	ds_read_b128 v[128:131], v67 offset:240
	s_waitcnt lgkmcnt(11)
	v_pk_fma_f32 v[186:187], v[24:25], v[132:133], v[186:187]
	v_pk_fma_f32 v[188:189], v[26:27], v[134:135], v[188:189]
	ds_read_b128 v[132:135], v67 offset:33792
	s_waitcnt lgkmcnt(11)
	v_pk_fma_f32 v[186:187], v[16:17], v[136:137], v[186:187]
	v_pk_fma_f32 v[188:189], v[18:19], v[138:139], v[188:189]
	ds_read_b128 v[136:139], v67 offset:33808
	s_waitcnt lgkmcnt(11)
	v_pk_fma_f32 v[186:187], v[20:21], v[140:141], v[186:187]
	v_pk_fma_f32 v[188:189], v[22:23], v[142:143], v[188:189]
	ds_read_b128 v[140:143], v67 offset:33824
	s_waitcnt lgkmcnt(11)
	v_pk_fma_f32 v[186:187], v[12:13], v[144:145], v[186:187]
	v_pk_fma_f32 v[188:189], v[14:15], v[146:147], v[188:189]
	ds_read_b128 v[144:147], v67 offset:33840
	s_waitcnt lgkmcnt(11)
	v_pk_fma_f32 v[186:187], v[48:49], v[148:149], v[186:187]
	v_pk_fma_f32 v[188:189], v[50:51], v[150:151], v[188:189]
	ds_read_b128 v[148:151], v67 offset:33856
	s_waitcnt lgkmcnt(11)
	v_pk_fma_f32 v[186:187], v[32:33], v[152:153], v[186:187]
	v_pk_fma_f32 v[188:189], v[34:35], v[154:155], v[188:189]
	ds_read_b128 v[152:155], v67 offset:33872
	s_waitcnt lgkmcnt(11)
	v_pk_fma_f32 v[186:187], v[52:53], v[156:157], v[186:187]
	v_pk_fma_f32 v[188:189], v[54:55], v[158:159], v[188:189]
	ds_read_b128 v[156:159], v67 offset:33888
	s_waitcnt lgkmcnt(11)
	v_pk_fma_f32 v[186:187], v[36:37], v[160:161], v[186:187]
	v_pk_fma_f32 v[188:189], v[38:39], v[162:163], v[188:189]
	ds_read_b128 v[160:163], v67 offset:33904
	s_waitcnt lgkmcnt(11)
	v_pk_fma_f32 v[186:187], v[56:57], v[116:117], v[186:187]
	v_pk_fma_f32 v[188:189], v[58:59], v[118:119], v[188:189]
	ds_read_b128 v[116:119], v67 offset:33920
	s_waitcnt lgkmcnt(11)
	v_pk_fma_f32 v[186:187], v[40:41], v[120:121], v[186:187]
	v_pk_fma_f32 v[188:189], v[42:43], v[122:123], v[188:189]
	ds_read_b128 v[120:123], v67 offset:33936
	s_waitcnt lgkmcnt(11)
	v_pk_fma_f32 v[186:187], v[60:61], v[124:125], v[186:187]
	v_pk_fma_f32 v[188:189], v[62:63], v[126:127], v[188:189]
	ds_read_b128 v[124:127], v67 offset:33952
	s_waitcnt lgkmcnt(11)
	v_pk_fma_f32 v[186:187], v[44:45], v[128:129], v[186:187]
	v_pk_fma_f32 v[188:189], v[46:47], v[130:131], v[188:189]
	ds_read_b128 v[128:131], v67 offset:33968
	s_waitcnt lgkmcnt(11)
	v_pk_mul_f32 v[190:191], v[28:29], v[132:133]
	v_pk_mul_f32 v[192:193], v[30:31], v[134:135]
	ds_read_b128 v[132:135], v67 offset:33984
	s_waitcnt lgkmcnt(11)
	v_pk_fma_f32 v[190:191], v[8:9], v[136:137], v[190:191]
	v_pk_fma_f32 v[192:193], v[10:11], v[138:139], v[192:193]
	ds_read_b128 v[136:139], v67 offset:34000
	s_waitcnt lgkmcnt(11)
	v_pk_fma_f32 v[190:191], v[4:5], v[140:141], v[190:191]
	v_pk_fma_f32 v[192:193], v[6:7], v[142:143], v[192:193]
	ds_read_b128 v[140:143], v67 offset:34016
	s_waitcnt lgkmcnt(11)
	v_pk_fma_f32 v[190:191], v[0:1], v[144:145], v[190:191]
	v_pk_fma_f32 v[192:193], v[2:3], v[146:147], v[192:193]
	ds_read_b128 v[144:147], v67 offset:34032
	s_waitcnt lgkmcnt(11)
	v_pk_fma_f32 v[190:191], v[24:25], v[148:149], v[190:191]
	v_pk_fma_f32 v[192:193], v[26:27], v[150:151], v[192:193]
	s_waitcnt lgkmcnt(10)
	v_pk_fma_f32 v[190:191], v[16:17], v[152:153], v[190:191]
	v_pk_fma_f32 v[192:193], v[18:19], v[154:155], v[192:193]
	s_waitcnt lgkmcnt(9)
	v_pk_fma_f32 v[190:191], v[20:21], v[156:157], v[190:191]
	v_pk_fma_f32 v[192:193], v[22:23], v[158:159], v[192:193]
	s_waitcnt lgkmcnt(8)
	v_pk_fma_f32 v[190:191], v[12:13], v[160:161], v[190:191]
	v_pk_fma_f32 v[192:193], v[14:15], v[162:163], v[192:193]
	s_waitcnt lgkmcnt(7)
	v_pk_fma_f32 v[190:191], v[48:49], v[116:117], v[190:191]
	v_pk_fma_f32 v[192:193], v[50:51], v[118:119], v[192:193]
	s_waitcnt lgkmcnt(6)
	v_pk_fma_f32 v[190:191], v[32:33], v[120:121], v[190:191]
	v_pk_fma_f32 v[192:193], v[34:35], v[122:123], v[192:193]
	s_waitcnt lgkmcnt(5)
	v_pk_fma_f32 v[190:191], v[52:53], v[124:125], v[190:191]
	v_pk_fma_f32 v[192:193], v[54:55], v[126:127], v[192:193]
	s_waitcnt lgkmcnt(4)
	v_pk_fma_f32 v[190:191], v[36:37], v[128:129], v[190:191]
	v_pk_fma_f32 v[192:193], v[38:39], v[130:131], v[192:193]
	s_waitcnt lgkmcnt(3)
	v_pk_fma_f32 v[190:191], v[56:57], v[132:133], v[190:191]
	v_pk_fma_f32 v[192:193], v[58:59], v[134:135], v[192:193]
	s_waitcnt lgkmcnt(2)
	v_pk_fma_f32 v[190:191], v[40:41], v[136:137], v[190:191]
	v_pk_fma_f32 v[192:193], v[42:43], v[138:139], v[192:193]
	s_waitcnt lgkmcnt(1)
	v_pk_fma_f32 v[190:191], v[60:61], v[140:141], v[190:191]
	v_pk_fma_f32 v[192:193], v[62:63], v[142:143], v[192:193]
	s_waitcnt lgkmcnt(0)
	v_pk_fma_f32 v[190:191], v[44:45], v[144:145], v[190:191]
	v_pk_fma_f32 v[192:193], v[46:47], v[146:147], v[192:193]
	v_add_f32_e32 v186, v186, v187
	v_add_f32_e32 v188, v188, v189
	v_add_f32_e32 v68, v186, v188
	v_add_f32_e32 v190, v190, v191
	v_add_f32_e32 v192, v192, v193
	v_add_f32_e32 v67, v190, v192
	v_mul_f32_e32 v71, v198, v199
	s_nop 1
	v_add_f32_dpp v71, v71, v71 quad_perm:[1,0,3,2] row_mask:0xf bank_mask:0xf
	s_nop 1
	v_add_f32_dpp v71, v71, v71 quad_perm:[2,3,0,1] row_mask:0xf bank_mask:0xf
	s_nop 1
	v_add_f32_dpp v71, v71, v71 row_half_mirror row_mask:0xf bank_mask:0xf
	s_nop 1
	v_add_f32_dpp v71, v71, v71 row_mirror row_mask:0xf bank_mask:0xf
	s_nop 1
	v_readlane_b32 s20, v71, 0
	v_readlane_b32 s21, v71, 16
	v_readlane_b32 s40, v71, 32
	v_readlane_b32 s41, v71, 48
	v_mov_b32_e32 v72, s20
	v_add_f32_e32 v72, s21, v72
	v_add_f32_e32 v72, s40, v72
	v_add_f32_e32 v71, s41, v72
	v_fma_f32 v68, -v66, v69, v68
	v_fma_f32 v67, -v66, v70, v67
	s_mul_i32 s13, s10, 0x210
	s_add_i32 s16, s13, 0
	s_add_i32 s16, s16, 0x21420
	v_mov_b32_e32 v0, v71
	v_fmac_f32_e32 v0, 0x80000000, v66
	v_cndmask_b32_e32 v2, v243, v0, vcc
	s_waitcnt vmcnt(0)
	v_mul_f32_e32 v0, 0x3fb8aa3b, v65
	v_max_f32_e32 v1, v2, v0
	v_max3_f32 v1, v68, v67, v1
	s_nop 1
	v_max_f32_dpp v1, v1, v1 quad_perm:[1,0,3,2] row_mask:0xf bank_mask:0xf
	s_nop 1
	v_max_f32_dpp v1, v1, v1 quad_perm:[2,3,0,1] row_mask:0xf bank_mask:0xf
	s_nop 1
	v_max_f32_dpp v1, v1, v1 row_half_mirror row_mask:0xf bank_mask:0xf
	s_nop 1
	v_max_f32_dpp v1, v1, v1 row_mirror row_mask:0xf bank_mask:0xf
	s_nop 1
	v_readlane_b32 s20, v1, 0
	v_readlane_b32 s21, v1, 16
	v_readlane_b32 s40, v1, 32
	v_readlane_b32 s41, v1, 48
	v_mov_b32_e32 v4, s20
	v_max_f32_e32 v4, s21, v4
	v_max_f32_e32 v4, s40, v4
	v_max_f32_e32 v1, s41, v4
	v_sub_f32_e32 v4, v68, v1
	v_exp_f32_e32 v10, v4
	v_sub_f32_e32 v11, v67, v1
	v_exp_f32_e32 v11, v11
	v_sub_f32_e32 v2, v2, v1
	v_add_f32_e32 v4, 0, v10
	v_add_f32_e32 v12, v11, v4
	v_exp_f32_e32 v4, v2
	s_nop 0
	v_add_f32_e32 v2, v4, v12
	s_nop 1
	v_add_f32_dpp v2, v2, v2 quad_perm:[1,0,3,2] row_mask:0xf bank_mask:0xf
	s_nop 1
	v_add_f32_dpp v2, v2, v2 quad_perm:[2,3,0,1] row_mask:0xf bank_mask:0xf
	s_nop 1
	v_add_f32_dpp v2, v2, v2 row_half_mirror row_mask:0xf bank_mask:0xf
	s_nop 1
	v_add_f32_dpp v2, v2, v2 row_mirror row_mask:0xf bank_mask:0xf
	s_nop 1
	v_readlane_b32 s20, v2, 0
	v_readlane_b32 s21, v2, 16
	v_readlane_b32 s40, v2, 32
	v_readlane_b32 s41, v2, 48
	v_mov_b32_e32 v3, s20
	v_add_f32_e32 v3, s21, v3
	v_add_f32_e32 v3, s40, v3
	v_add_f32_e32 v2, s41, v3
	v_mov_b32_e32 v3, 0
	v_lshl_add_u32 v5, v64, 2, s16
	ds_write2st64_b32 v5, v10, v11 offset1:1
	s_and_saveexec_b64 s[10:11], vcc
	v_mov_b32_e32 v5, s16
	ds_write_b32 v5, v4 offset:512
	s_or_b64 exec, exec, s[10:11]
	s_waitcnt lgkmcnt(0)
	s_add_i32 s10, s12, 0x10a10
	v_lshlrev_b32_e32 v149, 2, v64
	v_add_u32_e32 v149, s10, v149
	v_add_u32_e32 v150, 0x400, v149
	v_add_u32_e32 v151, 0x800, v149
	v_add_u32_e32 v152, 0xc00, v149
	s_add_i32 s11, s13, 0x21420
	v_mov_b32_e32 v148, s11
	v_mov_b32_e32 v4, 0
	v_mov_b32_e32 v5, 0
	v_mov_b32_e32 v6, 0
	v_mov_b32_e32 v7, 0
	ds_read_b128 v[116:119], v148
	ds_read_b128 v[120:123], v148 offset:16
	ds_read2_b32 v[124:125], v149 offset1:132
	ds_read2_b32 v[126:127], v150 offset0:8 offset1:140
	ds_read2_b32 v[128:129], v151 offset0:16 offset1:148
	ds_read2_b32 v[130:131], v152 offset0:24 offset1:156
	v_add_u32_e32 v149, 0x1080, v149
	v_add_u32_e32 v150, 0x1080, v150
	v_add_u32_e32 v151, 0x1080, v151
	v_add_u32_e32 v152, 0x1080, v152
	ds_read_b128 v[132:135], v148 offset:32
	ds_read_b128 v[136:139], v148 offset:48
	ds_read2_b32 v[140:141], v149 offset1:132
	ds_read2_b32 v[142:143], v150 offset0:8 offset1:140
	ds_read2_b32 v[144:145], v151 offset0:16 offset1:148
	ds_read2_b32 v[146:147], v152 offset0:24 offset1:156
	v_add_u32_e32 v149, 0x1080, v149
	v_add_u32_e32 v150, 0x1080, v150
	v_add_u32_e32 v151, 0x1080, v151
	v_add_u32_e32 v152, 0x1080, v152
	s_waitcnt lgkmcnt(6)
	v_pk_fma_f32 v[4:5], v[116:117], v[124:125], v[4:5]
	v_pk_fma_f32 v[6:7], v[118:119], v[126:127], v[6:7]
	v_pk_fma_f32 v[4:5], v[120:121], v[128:129], v[4:5]
	v_pk_fma_f32 v[6:7], v[122:123], v[130:131], v[6:7]
	ds_read_b128 v[116:119], v148 offset:64
	ds_read_b128 v[120:123], v148 offset:80
	ds_read2_b32 v[124:125], v149 offset1:132
	ds_read2_b32 v[126:127], v150 offset0:8 offset1:140
	ds_read2_b32 v[128:129], v151 offset0:16 offset1:148
	ds_read2_b32 v[130:131], v152 offset0:24 offset1:156
	v_add_u32_e32 v149, 0x1080, v149
	v_add_u32_e32 v150, 0x1080, v150
	v_add_u32_e32 v151, 0x1080, v151
	v_add_u32_e32 v152, 0x1080, v152
	s_waitcnt lgkmcnt(6)
	v_pk_fma_f32 v[4:5], v[132:133], v[140:141], v[4:5]
	v_pk_fma_f32 v[6:7], v[134:135], v[142:143], v[6:7]
	v_pk_fma_f32 v[4:5], v[136:137], v[144:145], v[4:5]
	v_pk_fma_f32 v[6:7], v[138:139], v[146:147], v[6:7]
	ds_read_b128 v[132:135], v148 offset:96
	ds_read_b128 v[136:139], v148 offset:112
	ds_read2_b32 v[140:141], v149 offset1:132
	ds_read2_b32 v[142:143], v150 offset0:8 offset1:140
	ds_read2_b32 v[144:145], v151 offset0:16 offset1:148
	ds_read2_b32 v[146:147], v152 offset0:24 offset1:156
	v_add_u32_e32 v149, 0x1080, v149
	v_add_u32_e32 v150, 0x1080, v150
	v_add_u32_e32 v151, 0x1080, v151
	v_add_u32_e32 v152, 0x1080, v152
	s_waitcnt lgkmcnt(6)
	v_pk_fma_f32 v[4:5], v[116:117], v[124:125], v[4:5]
	v_pk_fma_f32 v[6:7], v[118:119], v[126:127], v[6:7]
	v_pk_fma_f32 v[4:5], v[120:121], v[128:129], v[4:5]
	v_pk_fma_f32 v[6:7], v[122:123], v[130:131], v[6:7]
	ds_read_b128 v[116:119], v148 offset:128
	ds_read_b128 v[120:123], v148 offset:144
	ds_read2_b32 v[124:125], v149 offset1:132
	ds_read2_b32 v[126:127], v150 offset0:8 offset1:140
	ds_read2_b32 v[128:129], v151 offset0:16 offset1:148
	ds_read2_b32 v[130:131], v152 offset0:24 offset1:156
	v_add_u32_e32 v149, 0x1080, v149
	v_add_u32_e32 v150, 0x1080, v150
	v_add_u32_e32 v151, 0x1080, v151
	v_add_u32_e32 v152, 0x1080, v152
	s_waitcnt lgkmcnt(6)
	v_pk_fma_f32 v[4:5], v[132:133], v[140:141], v[4:5]
	v_pk_fma_f32 v[6:7], v[134:135], v[142:143], v[6:7]
	v_pk_fma_f32 v[4:5], v[136:137], v[144:145], v[4:5]
	v_pk_fma_f32 v[6:7], v[138:139], v[146:147], v[6:7]
	ds_read_b128 v[132:135], v148 offset:160
	ds_read_b128 v[136:139], v148 offset:176
	ds_read2_b32 v[140:141], v149 offset1:132
	ds_read2_b32 v[142:143], v150 offset0:8 offset1:140
	ds_read2_b32 v[144:145], v151 offset0:16 offset1:148
	ds_read2_b32 v[146:147], v152 offset0:24 offset1:156
	v_add_u32_e32 v149, 0x1080, v149
	v_add_u32_e32 v150, 0x1080, v150
	v_add_u32_e32 v151, 0x1080, v151
	v_add_u32_e32 v152, 0x1080, v152
	s_waitcnt lgkmcnt(6)
	v_pk_fma_f32 v[4:5], v[116:117], v[124:125], v[4:5]
	v_pk_fma_f32 v[6:7], v[118:119], v[126:127], v[6:7]
	v_pk_fma_f32 v[4:5], v[120:121], v[128:129], v[4:5]
	v_pk_fma_f32 v[6:7], v[122:123], v[130:131], v[6:7]
	ds_read_b128 v[116:119], v148 offset:192
	ds_read_b128 v[120:123], v148 offset:208
	ds_read2_b32 v[124:125], v149 offset1:132
	ds_read2_b32 v[126:127], v150 offset0:8 offset1:140
	ds_read2_b32 v[128:129], v151 offset0:16 offset1:148
	ds_read2_b32 v[130:131], v152 offset0:24 offset1:156
	v_add_u32_e32 v149, 0x1080, v149
	v_add_u32_e32 v150, 0x1080, v150
	v_add_u32_e32 v151, 0x1080, v151
	v_add_u32_e32 v152, 0x1080, v152
	s_waitcnt lgkmcnt(6)
	v_pk_fma_f32 v[4:5], v[132:133], v[140:141], v[4:5]
	v_pk_fma_f32 v[6:7], v[134:135], v[142:143], v[6:7]
	v_pk_fma_f32 v[4:5], v[136:137], v[144:145], v[4:5]
	v_pk_fma_f32 v[6:7], v[138:139], v[146:147], v[6:7]
	ds_read_b128 v[132:135], v148 offset:224
	ds_read_b128 v[136:139], v148 offset:240
	ds_read2_b32 v[140:141], v149 offset1:132
	ds_read2_b32 v[142:143], v150 offset0:8 offset1:140
	ds_read2_b32 v[144:145], v151 offset0:16 offset1:148
	ds_read2_b32 v[146:147], v152 offset0:24 offset1:156
	v_add_u32_e32 v149, 0x1080, v149
	v_add_u32_e32 v150, 0x1080, v150
	v_add_u32_e32 v151, 0x1080, v151
	v_add_u32_e32 v152, 0x1080, v152
	s_waitcnt lgkmcnt(6)
	v_pk_fma_f32 v[4:5], v[116:117], v[124:125], v[4:5]
	v_pk_fma_f32 v[6:7], v[118:119], v[126:127], v[6:7]
	v_pk_fma_f32 v[4:5], v[120:121], v[128:129], v[4:5]
	v_pk_fma_f32 v[6:7], v[122:123], v[130:131], v[6:7]
	ds_read_b128 v[116:119], v148 offset:256
	ds_read_b128 v[120:123], v148 offset:272
	ds_read2_b32 v[124:125], v149 offset1:132
	ds_read2_b32 v[126:127], v150 offset0:8 offset1:140
	ds_read2_b32 v[128:129], v151 offset0:16 offset1:148
	ds_read2_b32 v[130:131], v152 offset0:24 offset1:156
	v_add_u32_e32 v149, 0x1080, v149
	v_add_u32_e32 v150, 0x1080, v150
	v_add_u32_e32 v151, 0x1080, v151
	v_add_u32_e32 v152, 0x1080, v152
	s_waitcnt lgkmcnt(6)
	v_pk_fma_f32 v[4:5], v[132:133], v[140:141], v[4:5]
	v_pk_fma_f32 v[6:7], v[134:135], v[142:143], v[6:7]
	v_pk_fma_f32 v[4:5], v[136:137], v[144:145], v[4:5]
	v_pk_fma_f32 v[6:7], v[138:139], v[146:147], v[6:7]
	ds_read_b128 v[132:135], v148 offset:288
	ds_read_b128 v[136:139], v148 offset:304
	ds_read2_b32 v[140:141], v149 offset1:132
	ds_read2_b32 v[142:143], v150 offset0:8 offset1:140
	ds_read2_b32 v[144:145], v151 offset0:16 offset1:148
	ds_read2_b32 v[146:147], v152 offset0:24 offset1:156
	v_add_u32_e32 v149, 0x1080, v149
	v_add_u32_e32 v150, 0x1080, v150
	v_add_u32_e32 v151, 0x1080, v151
	v_add_u32_e32 v152, 0x1080, v152
	s_waitcnt lgkmcnt(6)
	v_pk_fma_f32 v[4:5], v[116:117], v[124:125], v[4:5]
	v_pk_fma_f32 v[6:7], v[118:119], v[126:127], v[6:7]
	v_pk_fma_f32 v[4:5], v[120:121], v[128:129], v[4:5]
	v_pk_fma_f32 v[6:7], v[122:123], v[130:131], v[6:7]
	ds_read_b128 v[116:119], v148 offset:320
	ds_read_b128 v[120:123], v148 offset:336
	ds_read2_b32 v[124:125], v149 offset1:132
	ds_read2_b32 v[126:127], v150 offset0:8 offset1:140
	ds_read2_b32 v[128:129], v151 offset0:16 offset1:148
	ds_read2_b32 v[130:131], v152 offset0:24 offset1:156
	v_add_u32_e32 v149, 0x1080, v149
	v_add_u32_e32 v150, 0x1080, v150
	v_add_u32_e32 v151, 0x1080, v151
	v_add_u32_e32 v152, 0x1080, v152
	s_waitcnt lgkmcnt(6)
	v_pk_fma_f32 v[4:5], v[132:133], v[140:141], v[4:5]
	v_pk_fma_f32 v[6:7], v[134:135], v[142:143], v[6:7]
	v_pk_fma_f32 v[4:5], v[136:137], v[144:145], v[4:5]
	v_pk_fma_f32 v[6:7], v[138:139], v[146:147], v[6:7]
	ds_read_b128 v[132:135], v148 offset:352
	ds_read_b128 v[136:139], v148 offset:368
	ds_read2_b32 v[140:141], v149 offset1:132
	ds_read2_b32 v[142:143], v150 offset0:8 offset1:140
	ds_read2_b32 v[144:145], v151 offset0:16 offset1:148
	ds_read2_b32 v[146:147], v152 offset0:24 offset1:156
	v_add_u32_e32 v149, 0x1080, v149
	v_add_u32_e32 v150, 0x1080, v150
	v_add_u32_e32 v151, 0x1080, v151
	v_add_u32_e32 v152, 0x1080, v152
	s_waitcnt lgkmcnt(6)
	v_pk_fma_f32 v[4:5], v[116:117], v[124:125], v[4:5]
	v_pk_fma_f32 v[6:7], v[118:119], v[126:127], v[6:7]
	v_pk_fma_f32 v[4:5], v[120:121], v[128:129], v[4:5]
	v_pk_fma_f32 v[6:7], v[122:123], v[130:131], v[6:7]
	ds_read_b128 v[116:119], v148 offset:384
	ds_read_b128 v[120:123], v148 offset:400
	ds_read2_b32 v[124:125], v149 offset1:132
	ds_read2_b32 v[126:127], v150 offset0:8 offset1:140
	ds_read2_b32 v[128:129], v151 offset0:16 offset1:148
	ds_read2_b32 v[130:131], v152 offset0:24 offset1:156
	v_add_u32_e32 v149, 0x1080, v149
	v_add_u32_e32 v150, 0x1080, v150
	v_add_u32_e32 v151, 0x1080, v151
	v_add_u32_e32 v152, 0x1080, v152
	s_waitcnt lgkmcnt(6)
	v_pk_fma_f32 v[4:5], v[132:133], v[140:141], v[4:5]
	v_pk_fma_f32 v[6:7], v[134:135], v[142:143], v[6:7]
	v_pk_fma_f32 v[4:5], v[136:137], v[144:145], v[4:5]
	v_pk_fma_f32 v[6:7], v[138:139], v[146:147], v[6:7]
	ds_read_b128 v[132:135], v148 offset:416
	ds_read_b128 v[136:139], v148 offset:432
	ds_read2_b32 v[140:141], v149 offset1:132
	ds_read2_b32 v[142:143], v150 offset0:8 offset1:140
	ds_read2_b32 v[144:145], v151 offset0:16 offset1:148
	ds_read2_b32 v[146:147], v152 offset0:24 offset1:156
	v_add_u32_e32 v149, 0x1080, v149
	v_add_u32_e32 v150, 0x1080, v150
	v_add_u32_e32 v151, 0x1080, v151
	v_add_u32_e32 v152, 0x1080, v152
	s_waitcnt lgkmcnt(6)
	v_pk_fma_f32 v[4:5], v[116:117], v[124:125], v[4:5]
	v_pk_fma_f32 v[6:7], v[118:119], v[126:127], v[6:7]
	v_pk_fma_f32 v[4:5], v[120:121], v[128:129], v[4:5]
	v_pk_fma_f32 v[6:7], v[122:123], v[130:131], v[6:7]
	ds_read_b128 v[116:119], v148 offset:448
	ds_read_b128 v[120:123], v148 offset:464
	ds_read2_b32 v[124:125], v149 offset1:132
	ds_read2_b32 v[126:127], v150 offset0:8 offset1:140
	ds_read2_b32 v[128:129], v151 offset0:16 offset1:148
	ds_read2_b32 v[130:131], v152 offset0:24 offset1:156
	v_add_u32_e32 v149, 0x1080, v149
	v_add_u32_e32 v150, 0x1080, v150
	v_add_u32_e32 v151, 0x1080, v151
	v_add_u32_e32 v152, 0x1080, v152
	s_waitcnt lgkmcnt(6)
	v_pk_fma_f32 v[4:5], v[132:133], v[140:141], v[4:5]
	v_pk_fma_f32 v[6:7], v[134:135], v[142:143], v[6:7]
	v_pk_fma_f32 v[4:5], v[136:137], v[144:145], v[4:5]
	v_pk_fma_f32 v[6:7], v[138:139], v[146:147], v[6:7]
	ds_read_b128 v[132:135], v148 offset:480
	ds_read_b128 v[136:139], v148 offset:496
	ds_read2_b32 v[140:141], v149 offset1:132
	ds_read2_b32 v[142:143], v150 offset0:8 offset1:140
	ds_read2_b32 v[144:145], v151 offset0:16 offset1:148
	ds_read2_b32 v[146:147], v152 offset0:24 offset1:156
	v_add_u32_e32 v149, 0x1080, v149
	v_add_u32_e32 v150, 0x1080, v150
	v_add_u32_e32 v151, 0x1080, v151
	v_add_u32_e32 v152, 0x1080, v152
	s_waitcnt lgkmcnt(6)
	v_pk_fma_f32 v[4:5], v[116:117], v[124:125], v[4:5]
	v_pk_fma_f32 v[6:7], v[118:119], v[126:127], v[6:7]
	v_pk_fma_f32 v[4:5], v[120:121], v[128:129], v[4:5]
	v_pk_fma_f32 v[6:7], v[122:123], v[130:131], v[6:7]
	ds_read_b32 v153, v148 offset:512
	ds_read_b32 v154, v149
	s_waitcnt lgkmcnt(2)
	v_pk_fma_f32 v[4:5], v[132:133], v[140:141], v[4:5]
	v_pk_fma_f32 v[6:7], v[134:135], v[142:143], v[6:7]
	v_pk_fma_f32 v[4:5], v[136:137], v[144:145], v[4:5]
	v_pk_fma_f32 v[6:7], v[138:139], v[146:147], v[6:7]
	s_waitcnt lgkmcnt(0)
	v_fmac_f32_e32 v4, v153, v154
	v_add_f32_e32 v4, v4, v5
	v_add_f32_e32 v6, v6, v7
	v_add_f32_e32 v4, v4, v6
